# fused retention-state loads split: 7 fragment tuples in registers of their own reloaded right after the MFMAs (full LRU iteration in flight), 5 in the scan window
# speedup vs baseline: 1.0155x; 1.0155x over previous
; #define ST_LOAD(KS, VS, mc_) do { const int _p0 = 128 * (mc_); _Pragma("unroll") for (int ks = 0; ks < 4; ++ks) { VS[ks] = *(const bf16x8*)(vbase + _p0 + 32 * ks + 8 * fq); \
;         _Pragma("unroll") for (int t = 0; t < 2; ++t) KS[ks][t] = *(const bf16x8*)(kbase + (size_t)(16 * t) * TB + _p0 + 32 * ks + 8 * fq); } } while (0)
; __device__ __forceinline__ void ret_state_item(const Args& A, Frame& F, int l, int it) {
;     ...
;     ST_LOAD(ka, va, ST_MC(0));
.Lfz_mc_pre:
	s_lshl_b32 s101, s100, 8
	s_add_u32 s98, s30, 0xd8c8000
	s_addc_u32 s99, s31, 0
	s_add_u32 s98, s98, s101
	s_addc_u32 s99, s99, 0
	global_load_dwordx4 v[98:101], v242, s[98:99]
	global_load_dwordx4 v[104:107], v242, s[98:99] offset:64
	global_load_dwordx4 v[108:111], v242, s[98:99] offset:128
	global_load_dwordx4 v[112:115], v242, s[98:99] offset:192
	s_sub_u32 s98, s98, 0x1200000
	s_subb_u32 s99, s99, 0
	global_load_dwordx4 v[116:119], v169, s[98:99]
	global_load_dwordx4 v[120:123], v169, s[98:99] offset:64
	global_load_dwordx4 v[124:127], v169, s[98:99] offset:128
	global_load_dwordx4 v[190:193], v169, s[98:99] offset:192
	s_add_u32 s98, s98, 0x12000
	s_addc_u32 s99, s99, 0
	global_load_dwordx4 v[194:197], v169, s[98:99]
	global_load_dwordx4 v[198:201], v169, s[98:99] offset:64
	global_load_dwordx4 v[202:205], v169, s[98:99] offset:128
	global_load_dwordx4 v[206:209], v169, s[98:99] offset:192
	s_branch .LBB0_63

; #define ST_LOAD(KS, VS, mc_) do { const int _p0 = 128 * (mc_); _Pragma("unroll") for (int ks = 0; ks < 4; ++ks) { VS[ks] = *(const bf16x8*)(vbase + _p0 + 32 * ks + 8 * fq); \
;         _Pragma("unroll") for (int t = 0; t < 2; ++t) KS[ks][t] = *(const bf16x8*)(kbase + (size_t)(16 * t) * TB + _p0 + 32 * ks + 8 * fq); } } while (0)
; #define ST_STORE(mc_) do { bf16_t* stp = WSB(WS_ST) + ((((size_t)(b * NH + h) * 2 + dir) * NCH + (mc_)) * DV + dvrow) * DK + 32 * dkh + 4 * fq; \
;         _Pragma("unroll") for (int t = 0; t < 2; ++t) { u32x2 o; o.x = pk2(acc[t][0], acc[t][1]); o.y = pk2(acc[t][2], acc[t][3]); *(u32x2*)(stp + 16 * t) = o; } } while (0)
; #define ST_COMPUTE(KS, VS) do { acc[0] *= cdec; acc[1] *= cdec; _Pragma("unroll") for (int ks = 0; ks < 4; ++ks) { const bf16x8 bv = scale8(VS[ks], dec[ks]); \
;         _Pragma("unroll") for (int t = 0; t < 2; ++t) acc[t] = __builtin_amdgcn_mfma_f32_16x16x32_bf16(KS[ks][t], bv, acc[t], 0, 0, 0); } } while (0)
; __device__ __forceinline__ void ret_state_item(const Args& A, Frame& F, int l, int it) {
;     ...
;     ST_LOAD(ka, va, ST_MC(0));
;     for (int s2 = 0; s2 < NCH; s2 += 2) {
;         ST_STORE(ST_MC(s2));
;         { const int sn = s2 + 1 < NCH - 1 ? s2 + 1 : NCH - 2; ST_LOAD(kb2, vb2, ST_MC(sn)); }
;         ST_COMPUTE(ka, va);
;         ST_STORE(ST_MC(s2 + 1));
;         if (s2 + 1 == NCH - 1) break;
;         { const int sn = s2 + 2 < NCH - 1 ? s2 + 2 : NCH - 2; ST_LOAD(ka, va, ST_MC(sn)); }
;         ST_COMPUTE(kb2, vb2);
.Lfz_mc_st:
	s_lshl_b32 s101, s100, 14
	s_add_u32 s98, s30, 0x1b0c8000
	s_addc_u32 s99, s31, 0
	s_add_u32 s98, s98, s101
	s_addc_u32 s99, s99, 0
	v_cvt_pk_bf16_f32 v250, v160, v161
	v_cvt_pk_bf16_f32 v251, v162, v163
	v_cvt_pk_bf16_f32 v252, v164, v165
	v_cvt_pk_bf16_f32 v253, v166, v167
	global_store_dwordx2 v243, v[250:251], s[98:99]
	global_store_dwordx2 v243, v[252:253], s[98:99] offset:32
	s_waitcnt vmcnt(9)
	s_cmp_eq_u32 s45, 18
	s_cbranch_scc1 .Lfz_skip
	v_pk_mul_f32 v[160:161], v[160:161], v[168:169] op_sel_hi:[1,0]
	v_pk_mul_f32 v[162:163], v[162:163], v[168:169] op_sel_hi:[1,0]
	v_pk_mul_f32 v[164:165], v[164:165], v[168:169] op_sel_hi:[1,0]
	v_pk_mul_f32 v[166:167], v[166:167], v[168:169] op_sel_hi:[1,0]
	v_lshlrev_b32_e32 v250, 16, v98
	v_and_b32_e32 v251, 0xffff0000, v98
	v_pk_mul_f32 v[250:251], v[250:251], v[152:153]
	v_cvt_pk_bf16_f32 v98, v250, v251
	v_lshlrev_b32_e32 v252, 16, v99
	v_and_b32_e32 v253, 0xffff0000, v99
	v_pk_mul_f32 v[252:253], v[252:253], v[154:155]
	v_cvt_pk_bf16_f32 v99, v252, v253
	v_lshlrev_b32_e32 v250, 16, v100
	v_and_b32_e32 v251, 0xffff0000, v100
	v_pk_mul_f32 v[250:251], v[250:251], v[156:157]
	v_cvt_pk_bf16_f32 v100, v250, v251
	v_lshlrev_b32_e32 v252, 16, v101
	v_and_b32_e32 v253, 0xffff0000, v101
	v_pk_mul_f32 v[252:253], v[252:253], v[158:159]
	v_cvt_pk_bf16_f32 v101, v252, v253
	v_lshlrev_b32_e32 v250, 16, v104
	v_and_b32_e32 v251, 0xffff0000, v104
	v_pk_mul_f32 v[250:251], v[250:251], v[152:153]
	v_pk_mul_f32 v[250:251], v[250:251], v[244:245] op_sel_hi:[1,0]
	v_cvt_pk_bf16_f32 v104, v250, v251
	v_lshlrev_b32_e32 v252, 16, v105
	v_and_b32_e32 v253, 0xffff0000, v105
	v_pk_mul_f32 v[252:253], v[252:253], v[154:155]
	v_pk_mul_f32 v[252:253], v[252:253], v[244:245] op_sel_hi:[1,0]
	v_cvt_pk_bf16_f32 v105, v252, v253
	v_lshlrev_b32_e32 v250, 16, v106
	v_and_b32_e32 v251, 0xffff0000, v106
	v_pk_mul_f32 v[250:251], v[250:251], v[156:157]
	v_pk_mul_f32 v[250:251], v[250:251], v[244:245] op_sel_hi:[1,0]
	v_cvt_pk_bf16_f32 v106, v250, v251
	v_lshlrev_b32_e32 v252, 16, v107
	v_and_b32_e32 v253, 0xffff0000, v107
	v_pk_mul_f32 v[252:253], v[252:253], v[158:159]
	v_pk_mul_f32 v[252:253], v[252:253], v[244:245] op_sel_hi:[1,0]
	v_cvt_pk_bf16_f32 v107, v252, v253
	v_lshlrev_b32_e32 v250, 16, v108
	v_and_b32_e32 v251, 0xffff0000, v108
	v_pk_mul_f32 v[250:251], v[250:251], v[152:153]
	v_pk_mul_f32 v[250:251], v[250:251], v[246:247] op_sel_hi:[1,0]
	v_cvt_pk_bf16_f32 v108, v250, v251
	v_lshlrev_b32_e32 v252, 16, v109
	v_and_b32_e32 v253, 0xffff0000, v109
	v_pk_mul_f32 v[252:253], v[252:253], v[154:155]
	v_pk_mul_f32 v[252:253], v[252:253], v[246:247] op_sel_hi:[1,0]
	v_cvt_pk_bf16_f32 v109, v252, v253
	v_lshlrev_b32_e32 v250, 16, v110
	v_and_b32_e32 v251, 0xffff0000, v110
	v_pk_mul_f32 v[250:251], v[250:251], v[156:157]
	v_pk_mul_f32 v[250:251], v[250:251], v[246:247] op_sel_hi:[1,0]
	v_cvt_pk_bf16_f32 v110, v250, v251
	v_lshlrev_b32_e32 v252, 16, v111
	v_and_b32_e32 v253, 0xffff0000, v111
	v_pk_mul_f32 v[252:253], v[252:253], v[158:159]
	v_pk_mul_f32 v[252:253], v[252:253], v[246:247] op_sel_hi:[1,0]
	v_cvt_pk_bf16_f32 v111, v252, v253
	v_lshlrev_b32_e32 v250, 16, v112
	v_and_b32_e32 v251, 0xffff0000, v112
	v_pk_mul_f32 v[250:251], v[250:251], v[152:153]
	v_pk_mul_f32 v[250:251], v[250:251], v[248:249] op_sel_hi:[1,0]
	v_cvt_pk_bf16_f32 v112, v250, v251
	v_lshlrev_b32_e32 v252, 16, v113
	v_and_b32_e32 v253, 0xffff0000, v113
	v_pk_mul_f32 v[252:253], v[252:253], v[154:155]
	v_pk_mul_f32 v[252:253], v[252:253], v[248:249] op_sel_hi:[1,0]
	v_cvt_pk_bf16_f32 v113, v252, v253
	v_lshlrev_b32_e32 v250, 16, v114
	v_and_b32_e32 v251, 0xffff0000, v114
	v_pk_mul_f32 v[250:251], v[250:251], v[156:157]
	v_pk_mul_f32 v[250:251], v[250:251], v[248:249] op_sel_hi:[1,0]
	v_cvt_pk_bf16_f32 v114, v250, v251
	v_lshlrev_b32_e32 v252, 16, v115
	v_and_b32_e32 v253, 0xffff0000, v115
	v_pk_mul_f32 v[252:253], v[252:253], v[158:159]
	v_pk_mul_f32 v[252:253], v[252:253], v[248:249] op_sel_hi:[1,0]
	v_cvt_pk_bf16_f32 v115, v252, v253
	s_nop 1
	v_mfma_f32_16x16x32_bf16 v[160:163], v[116:119], v[98:101], v[160:163]
	v_mfma_f32_16x16x32_bf16 v[164:167], v[194:197], v[98:101], v[164:167]
	v_mfma_f32_16x16x32_bf16 v[160:163], v[120:123], v[104:107], v[160:163]
	v_mfma_f32_16x16x32_bf16 v[164:167], v[198:201], v[104:107], v[164:167]
	v_mfma_f32_16x16x32_bf16 v[160:163], v[124:127], v[108:111], v[160:163]
	v_mfma_f32_16x16x32_bf16 v[164:167], v[202:205], v[108:111], v[164:167]
	v_mfma_f32_16x16x32_bf16 v[160:163], v[190:193], v[112:115], v[160:163]
	v_mfma_f32_16x16x32_bf16 v[164:167], v[206:209], v[112:115], v[164:167]
	s_min_u32 s100, s45, 16
	s_bfe_u32 s101, s37, 0x10001
	s_cmp_eq_u32 s101, 0
	s_cbranch_scc1 .Lfz_mc_e
	s_sub_i32 s101, 19, s100
	s_cmp_lt_u32 s100, 2
	s_cbranch_scc0 .Lfz_mc1_e
	s_sub_i32 s101, 1, s100

; #define ST_LOAD(KS, VS, mc_) do { const int _p0 = 128 * (mc_); _Pragma("unroll") for (int ks = 0; ks < 4; ++ks) { VS[ks] = *(const bf16x8*)(vbase + _p0 + 32 * ks + 8 * fq); \
;         _Pragma("unroll") for (int t = 0; t < 2; ++t) KS[ks][t] = *(const bf16x8*)(kbase + (size_t)(16 * t) * TB + _p0 + 32 * ks + 8 * fq); } } while (0)
; #define ST_STORE(mc_) do { bf16_t* stp = WSB(WS_ST) + ((((size_t)(b * NH + h) * 2 + dir) * NCH + (mc_)) * DV + dvrow) * DK + 32 * dkh + 4 * fq; \
;         _Pragma("unroll") for (int t = 0; t < 2; ++t) { u32x2 o; o.x = pk2(acc[t][0], acc[t][1]); o.y = pk2(acc[t][2], acc[t][3]); *(u32x2*)(stp + 16 * t) = o; } } while (0)
; #define ST_COMPUTE(KS, VS) do { acc[0] *= cdec; acc[1] *= cdec; _Pragma("unroll") for (int ks = 0; ks < 4; ++ks) { const bf16x8 bv = scale8(VS[ks], dec[ks]); \
;         _Pragma("unroll") for (int t = 0; t < 2; ++t) acc[t] = __builtin_amdgcn_mfma_f32_16x16x32_bf16(KS[ks][t], bv, acc[t], 0, 0, 0); } } while (0)
; __device__ __forceinline__ void ret_state_item(const Args& A, Frame& F, int l, int it) {
;     ...
;     ST_LOAD(ka, va, ST_MC(0));
;     for (int s2 = 0; s2 < NCH; s2 += 2) {
;         ST_STORE(ST_MC(s2));
;         { const int sn = s2 + 1 < NCH - 1 ? s2 + 1 : NCH - 2; ST_LOAD(kb2, vb2, ST_MC(sn)); }
;         ST_COMPUTE(ka, va);
;         ST_STORE(ST_MC(s2 + 1));
;         if (s2 + 1 == NCH - 1) break;
;         { const int sn = s2 + 2 < NCH - 1 ? s2 + 2 : NCH - 2; ST_LOAD(ka, va, ST_MC(sn)); }
.Lfz_mc_e:
	s_lshl_b32 s101, s100, 8
	s_add_u32 s98, s30, 0xd8c8000
	s_addc_u32 s99, s31, 0
	s_add_u32 s98, s98, s101
	s_addc_u32 s99, s99, 0
	global_load_dwordx4 v[98:101], v242, s[98:99]
	global_load_dwordx4 v[104:107], v242, s[98:99] offset:64
	global_load_dwordx4 v[108:111], v242, s[98:99] offset:128
	global_load_dwordx4 v[112:115], v242, s[98:99] offset:192
	s_sub_u32 s98, s98, 0x1200000
	s_subb_u32 s99, s99, 0
	global_load_dwordx4 v[116:119], v169, s[98:99]
	global_load_dwordx4 v[120:123], v169, s[98:99] offset:64
	global_load_dwordx4 v[124:127], v169, s[98:99] offset:128
	s_add_u32 s98, s98, 0x12000
	s_addc_u32 s99, s99, 0

; #define ST_LOAD(KS, VS, mc_) do { const int _p0 = 128 * (mc_); _Pragma("unroll") for (int ks = 0; ks < 4; ++ks) { VS[ks] = *(const bf16x8*)(vbase + _p0 + 32 * ks + 8 * fq); \
;         _Pragma("unroll") for (int t = 0; t < 2; ++t) KS[ks][t] = *(const bf16x8*)(kbase + (size_t)(16 * t) * TB + _p0 + 32 * ks + 8 * fq); } } while (0)
; #define ST_STORE(mc_) do { bf16_t* stp = WSB(WS_ST) + ((((size_t)(b * NH + h) * 2 + dir) * NCH + (mc_)) * DV + dvrow) * DK + 32 * dkh + 4 * fq; \
;         _Pragma("unroll") for (int t = 0; t < 2; ++t) { u32x2 o; o.x = pk2(acc[t][0], acc[t][1]); o.y = pk2(acc[t][2], acc[t][3]); *(u32x2*)(stp + 16 * t) = o; } } while (0)
; #define ST_COMPUTE(KS, VS) do { acc[0] *= cdec; acc[1] *= cdec; _Pragma("unroll") for (int ks = 0; ks < 4; ++ks) { const bf16x8 bv = scale8(VS[ks], dec[ks]); \
;         _Pragma("unroll") for (int t = 0; t < 2; ++t) acc[t] = __builtin_amdgcn_mfma_f32_16x16x32_bf16(KS[ks][t], bv, acc[t], 0, 0, 0); } } while (0)
; __device__ __forceinline__ void ret_state_item(const Args& A, Frame& F, int l, int it) {
;     ...
;     ST_LOAD(ka, va, ST_MC(0));
;     for (int s2 = 0; s2 < NCH; s2 += 2) {
;         ST_STORE(ST_MC(s2));
;         { const int sn = s2 + 1 < NCH - 1 ? s2 + 1 : NCH - 2; ST_LOAD(kb2, vb2, ST_MC(sn)); }
;         ST_COMPUTE(ka, va);
;         ST_STORE(ST_MC(s2 + 1));
;         if (s2 + 1 == NCH - 1) break;
;         { const int sn = s2 + 2 < NCH - 1 ? s2 + 2 : NCH - 2; ST_LOAD(ka, va, ST_MC(sn)); }
.Lfz_mc_nx:
	s_lshl_b32 s101, s100, 8
	s_add_u32 s98, s30, 0xd8c8000
	s_addc_u32 s99, s31, 0
	s_add_u32 s98, s98, s101
	s_addc_u32 s99, s99, 0
	s_sub_u32 s98, s98, 0x1200000
	s_subb_u32 s99, s99, 0
	global_load_dwordx4 v[190:193], v169, s[98:99] offset:192
	s_add_u32 s98, s98, 0x12000
	s_addc_u32 s99, s99, 0
	global_load_dwordx4 v[194:197], v169, s[98:99]
	global_load_dwordx4 v[198:201], v169, s[98:99] offset:64
	global_load_dwordx4 v[202:205], v169, s[98:99] offset:128
	global_load_dwordx4 v[206:209], v169, s[98:99] offset:192
